# GEMM per-block setprio toggles removed plus indexer work table short items re-dealt evenly (workgroups 0-63 shed ~6 tiles each to 192-255)
# speedup vs baseline: 1.0112x; 1.0112x over previous
; __device__ __forceinline__ void idx_phase(const Args& a, unsigned char* lds, int tid, int lane, int wave) {
;     ...
;     for (int kk = 0; ; ++kk) {
;         int id;
;         if (use_tab) { if (kk >= IDX_TAB_N) break; id = IDX_TAB[blockIdx.x][kk]; if (id == 0xFFFF) break; }
;         else { const int it = blockIdx.x + kk * gridDim.x; if (it >= 528) break;
;                id = it < 256 ? (255 - (it >> 1)) * 2 + (it & 1) : (it < 512 ? ((it - 256) >> 1) * 2 + (it & 1) : it); }
;         int c, half = id & 1, bb = 0; bool sample = false;
;         if (id < 512) c = id >> 1;
;         else { sample = true; bb = (id - 512) >> 1; c = 256 + bb; }
;         const int L = sample ? 1088 : 64 * (c + 1), ntile = L >> 6;
_ZL7IDX_TAB:
	.short	401
	.short	67
	.short	65535
	.short	416
	.short	64
	.short	65535
	.short	395
	.short	79
	.short	65535
	.short	393
	.short	73
	.short	65535
	.short	399
	.short	70
	.short	65535
	.short	390
	.short	78
	.short	65535
	.short	391
	.short	81
	.short	65535
	.short	410
	.short	65
	.short	65535
	.short	406
	.short	66
	.short	65535
	.short	384
	.short	92
	.short	65535
	.short	385
	.short	89
	.short	65535
	.short	377
	.short	102
	.short	65535
	.short	388
	.short	85
	.short	65535
	.short	378
	.short	99
	.short	65535
	.short	371
	.short	109
	.short	65535
	.short	381
	.short	94
	.short	65535
	.short	369
	.short	114
	.short	65535
	.short	370
	.short	110
	.short	65535
	.short	374
	.short	103
	.short	65535
	.short	364
	.short	118
	.short	65535
	.short	373
	.short	107
	.short	65535
	.short	362
	.short	121
	.short	65535
	.short	368
	.short	115
	.short	65535
	.short	354
	.short	134
	.short	65535
	.short	359
	.short	131
	.short	65535
	.short	363
	.short	123
	.short	65535
	.short	356
	.short	128
	.short	65535
	.short	358
	.short	127
	.short	65535
	.short	365
	.short	122
	.short	65535
	.short	360
	.short	133
	.short	65535
	.short	355
	.short	136
	.short	65535
	.short	353
	.short	140
	.short	65535
	.short	350
	.short	143
	.short	65535
	.short	352
	.short	137
	.short	65535
	.short	348
	.short	142
	.short	65535
	.short	347
	.short	146
	.short	65535
	.short	346
	.short	148
	.short	65535
	.short	349
	.short	145
	.short	65535
	.short	344
	.short	151
	.short	65535
	.short	345
	.short	152
	.short	65535
	.short	341
	.short	157
	.short	65535
	.short	343
	.short	153
	.short	65535
	.short	340
	.short	158
	.short	65535
	.short	342
	.short	154
	.short	65535
	.short	338
	.short	161
	.short	65535
	.short	339
	.short	160
	.short	65535
	.short	336
	.short	163
	.short	65535
	.short	337
	.short	164
	.short	65535
	.short	334
	.short	166
	.short	65535
	.short	335
	.short	167
	.short	65535
	.short	332
	.short	169
	.short	65535
	.short	333
	.short	171
	.short	65535
	.short	329
	.short	175
	.short	65535
	.short	331
	.short	170
	.short	65535
	.short	328
	.short	176
	.short	65535
	.short	330
	.short	172
	.short	65535
	.short	326
	.short	178
	.short	65535
	.short	327
	.short	180
	.short	65535
	.short	324
	.short	181
	.short	65535
	.short	325
	.short	177
	.short	65535
	.short	322
	.short	182
	.short	65535
	.short	323
	.short	183
	.short	65535
	.short	320
	.short	185
	.short	65535
	.short	321
	.short	186
	.short	65535
	.short	318
	.short	192
	.short	65535
	.short	319
	.short	193
	.short	65535
	.short	316
	.short	194
	.short	65535
	.short	317
	.short	195
	.short	65535
	.short	314
	.short	196
	.short	65535
	.short	315
	.short	197
	.short	65535
	.short	312
	.short	198
	.short	65535
	.short	313
	.short	199
	.short	65535
	.short	310
	.short	200
	.short	65535
	.short	311
	.short	201
	.short	65535
	.short	308
	.short	202
	.short	65535
	.short	309
	.short	203
	.short	65535
	.short	306
	.short	204
	.short	65535
	.short	307
	.short	205
	.short	65535
	.short	304
	.short	206
	.short	65535
	.short	305
	.short	207
	.short	65535
	.short	302
	.short	208
	.short	65535
	.short	303
	.short	209
	.short	65535
	.short	300
	.short	210
	.short	65535
	.short	301
	.short	211
	.short	65535
	.short	298
	.short	212
	.short	65535
	.short	299
	.short	213
	.short	65535
	.short	296
	.short	214
	.short	65535
	.short	297
	.short	215
	.short	65535
	.short	294
	.short	216
	.short	65535
	.short	295
	.short	217
	.short	65535
	.short	292
	.short	218
	.short	65535
	.short	293
	.short	219
	.short	65535
	.short	290
	.short	220
	.short	65535
	.short	291
	.short	221
	.short	65535
	.short	288
	.short	222
	.short	65535
	.short	289
	.short	223
	.short	65535
	.short	286
	.short	224
	.short	65535
	.short	287
	.short	225
	.short	65535
	.short	284
	.short	226
	.short	65535
	.short	285
	.short	227
	.short	65535
	.short	282
	.short	228
	.short	65535
	.short	283
	.short	229
	.short	65535
	.short	280
	.short	230
	.short	65535
	.short	281
	.short	231
	.short	65535
	.short	278
	.short	232
	.short	65535
	.short	279
	.short	233
	.short	65535
	.short	276
	.short	234
	.short	65535
	.short	277
	.short	235
	.short	65535
	.short	274
	.short	236
	.short	65535
	.short	275
	.short	237
	.short	65535
	.short	272
	.short	238
	.short	65535
	.short	273
	.short	239
	.short	65535
	.short	270
	.short	240
	.short	65535
	.short	271
	.short	241
	.short	65535
	.short	268
	.short	242
	.short	65535
	.short	269
	.short	243
	.short	65535
	.short	266
	.short	244
	.short	65535
	.short	267
	.short	245
	.short	65535
	.short	264
	.short	246
	.short	65535
	.short	265
	.short	247
	.short	65535
	.short	262
	.short	248
	.short	65535
	.short	263
	.short	249
	.short	65535
	.short	260
	.short	250
	.short	65535
	.short	261
	.short	251
	.short	65535
	.short	258
	.short	252
	.short	65535
	.short	259
	.short	253
	.short	65535
	.short	256
	.short	254
; __device__ __forceinline__ void idx_phase(const Args& a, unsigned char* lds, int tid, int lane, int wave) {
;     ...
;     for (int kk = 0; ; ++kk) {
;         int id;
;         if (use_tab) { if (kk >= IDX_TAB_N) break; id = IDX_TAB[blockIdx.x][kk]; if (id == 0xFFFF) break; }
;         else { const int it = blockIdx.x + kk * gridDim.x; if (it >= 528) break;
;                id = it < 256 ? (255 - (it >> 1)) * 2 + (it & 1) : (it < 512 ? ((it - 256) >> 1) * 2 + (it & 1) : it); }
;         int c, half = id & 1, bb = 0; bool sample = false;
;         if (id < 512) c = id >> 1;
;         else { sample = true; bb = (id - 512) >> 1; c = 256 + bb; }
;         const int L = sample ? 1088 : 64 * (c + 1), ntile = L >> 6;
	.short	65535
	.short	257
	.short	255
	.short	65535
	.short	508
	.short	16
	.short	65535
	.short	511
	.short	10
	.short	65535
	.short	510
	.short	12
	.short	65535
	.short	509
	.short	15
	.short	65535
	.short	506
	.short	20
	.short	65535
	.short	507
	.short	19
	.short	65535
	.short	504
	.short	22
	.short	65535
	.short	500
	.short	24
	.short	65535
	.short	502
	.short	23
	.short	65535
	.short	503
	.short	25
	.short	65535
	.short	505
	.short	21
	.short	65535
	.short	501
	.short	27
	.short	65535
	.short	498
	.short	18
	.short	65535
	.short	499
	.short	29
	.short	65535
	.short	496
	.short	30
	.short	65535
	.short	497
	.short	28
	.short	65535
	.short	491
	.short	526
	.short	65535
	.short	495
	.short	527
	.short	65535
	.short	492
	.short	524
	.short	65535
	.short	493
	.short	525
	.short	65535
	.short	490
	.short	522
	.short	65535
	.short	494
	.short	31
	.short	65535
	.short	488
	.short	520
	.short	65535
	.short	483
	.short	513
	.short	65535
	.short	486
	.short	518
	.short	65535
	.short	482
	.short	37
	.short	65535
	.short	484
	.short	516
	.short	65535
	.short	489
	.short	517
	.short	65535
	.short	487
	.short	514
	.short	65535
	.short	485
	.short	515
	.short	65535
	.short	480
	.short	38
	.short	65535
	.short	481
	.short	36
	.short	65535
	.short	478
	.short	32
	.short	9
	.short	479
	.short	35
	.short	3
	.short	472
	.short	521
	.short	17
	.short	463
	.short	519
	.short	26
	.short	474
	.short	523
	.short	11
	.short	476
	.short	512
	.short	13
	.short	475
	.short	33
	.short	8
	.short	439
	.short	42
	.short	34
	.short	470
	.short	40
	.short	6
	.short	471
	.short	39
	.short	7
	.short	467
	.short	45
	.short	4
	.short	469
	.short	43
	.short	5
	.short	466
	.short	47
	.short	2
	.short	458
	.short	46
	.short	14
	.short	464
	.short	51
	.short	0
	.short	465
	.short	49
	.short	1
	.short	468
	.short	48
	.short	65535
	.short	477
	.short	41
	.short	65535
	.short	460
	.short	50
	.short	65535
	.short	473
	.short	44
	.short	65535
	.short	462
	.short	52
	.short	65535
	.short	461
	.short	53
	.short	65535
	.short	456
	.short	57
	.short	65535
	.short	457
	.short	55
	.short	65535
	.short	454
	.short	56
	.short	65535
	.short	455
	.short	59
	.short	65535
	.short	452
	.short	58
	.short	65535
	.short	459
	.short	54
	.short	65535
	.short	453
	.short	60
	.short	65535
	.short	451
	.short	61
	.short	65535
	.short	448
	.short	62
	.short	65535
	.short	450
	.short	63
	.short	65535
	.short	449
	.short	68
	.short	65535
	.short	447
	.short	69
	.short	65535
	.short	444
	.short	71
	.short	65535
	.short	446
	.short	72
	.short	65535
	.short	442
	.short	75
	.short	65535
	.short	445
	.short	74
	.short	65535
	.short	443
	.short	76
	.short	65535
	.short	441
	.short	77
	.short	65535
	.short	438
	.short	83
	.short	65535
	.short	440
	.short	80
	.short	65535
	.short	436
	.short	82
	.short	65535
	.short	437
	.short	84
	.short	65535
	.short	434
	.short	86
	.short	65535
	.short	430
	.short	93
	.short	65535
	.short	435
	.short	87
	.short	65535
	.short	433
	.short	88
	.short	65535
	.short	432
	.short	91
	.short	65535
	.short	431
	.short	90
	.short	65535
	.short	428
	.short	95
	.short	65535
	.short	426
	.short	97
	.short	65535
	.short	429
	.short	96
	.short	65535
	.short	427
	.short	98
	.short	65535
	.short	424
	.short	101
	.short	65535
	.short	422
	.short	104
	.short	65535
	.short	425
	.short	100
	.short	65535
	.short	423
	.short	105
	.short	65535
	.short	418
	.short	111
	.short	65535
	.short	421
	.short	108
	.short	65535
	.short	420
	.short	106
	.short	65535
	.short	419
	.short	113
	.short	65535
	.short	413
	.short	116
	.short	65535
	.short	417
	.short	112
	.short	65535
	.short	407
	.short	129
	.short	65535
	.short	408
	.short	126
	.short	65535
	.short	414
	.short	119
	.short	65535
	.short	415
	.short	117
	.short	65535
	.short	403
	.short	135
	.short	65535
	.short	412
	.short	120
	.short	65535
	.short	411
	.short	125
	.short	65535
	.short	400
	.short	138
	.short	65535
	.short	404
	.short	130
	.short	65535
	.short	409
	.short	124
	.short	65535
	.short	398
	.short	141
	.short	65535
	.short	405
	.short	132
	.short	65535
	.short	402
	.short	139
	.short	65535
	.short	396
	.short	149
	.short	65535
	.short	392
	.short	150
	.short	65535
	.short	394
	.short	144
	.short	65535
	.short	383
	.short	162
	.short	65535
	.short	389
	.short	155
	.short	65535
	.short	387
	.short	156
	.short	65535
	.short	397
	.short	147
	.short	65535
	.short	386
	.short	159
	.short	65535
	.short	376
	.short	173
	.short	65535
	.short	375
	.short	179
	.short	65535
	.short	372
	.short	184
	.short	65535
	.short	380
	.short	168
	.short	65535
	.short	379
	.short	174
	.short	65535
	.short	382
	.short	165
	.short	65535
	.short	366
	.short	187
	.short	65535
	.short	357
	.short	190
	.short	65535
	.short	351
	.short	191
	.short	65535
	.short	361
	.short	189
	.short	65535
	.short	367
	.short	188
	.short	65535
	.size	_ZL7IDX_TAB, 1536

	.type	__hip_cuid_61d45634659d28aa,@object
